# attention-merge load prefetch on top of v31 (no rowss hoist)
# speedup vs baseline: 1.0282x; 1.0095x over previous
; #define LAS __attribute__((address_space(3)))
; __device__ __forceinline__ f32x4 mfma16(bf16x8 a, bf16x8 b, f32x4 c) { return __builtin_amdgcn_mfma_f32_16x16x32_bf16(a, b, c, 0, 0, 0); }
; __device__ __forceinline__ s16x4 vtr(const LAS unsigned char* p) { return __builtin_bit_cast(s16x4, __builtin_amdgcn_ds_read_tr16_b64_v4i16((LAS s16x4*)p)); }
; __device__ __forceinline__ bf16x8 pack8(f32x4 a, f32x4 b) { u32x4 w; w.x = cvtpk(a[0], a[1]); w.y = cvtpk(a[2], a[3]); w.z = cvtpk(b[0], b[1]); w.w = cvtpk(b[2], b[3]); return __builtin_bit_cast(bf16x8, w); }
; #define AU_DECODE(U_) do { int U = (U_); int bh; if (sel == 0) { if (U < 512) { bh = U >> 4; un = U & 15; ur = 1; urho = 0; uslot = 0; } \
;             else { U -= 512; bh = U >> 4; urho = (U >> 2) & 3; un = U & 3; ur = 4; uslot = 1; } } \
;         else { bh = U >> 4; urho = U & 15; un = 0; ur = 16; uslot = 0; } ub = bh >> 3; uh = bh & 7; } while (0)
; __device__ __forceinline__ void attn_units(const Params& p, LAS unsigned char* buf, int sel, int wave) {
;     ...
;         bf16x8 pf[5][2];
; #pragma unroll
;         for (int kk = 0; kk < 5; ++kk) { pf[kk][0] = pack8(sc[2 * kk][0], sc[2 * kk + 1][0]); pf[kk][1] = pack8(sc[2 * kk][1], sc[2 * kk + 1][1]); }
;         __syncthreads();
; #pragma unroll
;         for (int i = 0; i < 12; ++i) { const int pc = tid + 512 * i, row = pc >> 4, cc = pc & 15; *(LAS u32x4*)(buf + row * 288 + cc * 16) = kvreg[i]; }
;         __syncthreads();
;         if (k + 1 < nk) { AU_DECODE((int)blockIdx.x + G * (k + 1)); AU_KVLOAD(1); AU_QLOAD(); }
;         f32x4 oacc[8][2];
; #pragma unroll
;         for (int d = 0; d < 8; ++d) { oacc[d][0] = (f32x4){0.f, 0.f, 0.f, 0.f}; oacc[d][1] = (f32x4){0.f, 0.f, 0.f, 0.f}; }
; #pragma unroll
;         for (int kk = 0; kk < 5; ++kk) {
; #pragma unroll
;             for (int d = 0; d < 8; ++d) { const LAS unsigned char* ap = buf + (32 * wave + 32 * kk + 4 * g + (fr >> 2)) * 288 + (16 * d + 4 * (fr & 3)) * 2;
;                 const bf16x8 vf = cat8(vtr(ap), vtr(ap + 16 * 288));
;                 oacc[d][0] = mfma16(vf, pf[kk][0], oacc[d][0]); oacc[d][1] = mfma16(vf, pf[kk][1], oacc[d][1]); }
.LBB0_762:
	v_cvt_pk_bf16_f32 v108, v112, v116
	v_lshrrev_b32_e32 v116, 2, v163
	v_cvt_pk_bf16_f32 v109, v117, v118
	v_or_b32_e32 v117, v162, v116
	v_and_b32_e32 v116, 24, v197
	v_add_u32_e32 v116, 0, v116
	v_add_u32_e32 v118, s3, v117
	v_cvt_pk_bf16_f32 v114, v85, v86
	v_cvt_pk_bf16_f32 v85, v141, v142
	v_cvt_pk_bf16_f32 v86, v143, v144
	v_mad_u64_u32 v[142:143], s[4:5], v118, s12, v[116:117]
	v_add_f32_e32 v152, v100, v101
	v_cvt_pk_bf16_f32 v110, v119, v120
	v_cvt_pk_bf16_f32 v111, v122, v123
	v_cvt_pk_bf16_f32 v100, v121, v124
	v_cvt_pk_bf16_f32 v101, v125, v126
	ds_read_b64_tr_b16 v[120:121], v142 offset:4608
	ds_read_b64_tr_b16 v[118:119], v142
	ds_read_b64_tr_b16 v[122:123], v142 offset:32
	ds_read_b64_tr_b16 v[124:125], v142 offset:4640
	v_cvt_pk_bf16_f32 v112, v80, v81
	v_cvt_pk_bf16_f32 v113, v82, v84
	v_cvt_pk_bf16_f32 v106, v93, v94
	v_cvt_pk_bf16_f32 v93, v133, v134
	v_cvt_pk_bf16_f32 v94, v135, v136
	v_cvt_pk_bf16_f32 v84, v137, v140
	v_cvt_pk_bf16_f32 v81, v154, v155
	v_cvt_pk_bf16_f32 v82, v156, v157
	ds_read_b64_tr_b16 v[134:135], v142 offset:64
	ds_read_b64_tr_b16 v[136:137], v142 offset:4672
	ds_read_b64_tr_b16 v[154:155], v142 offset:96
	ds_read_b64_tr_b16 v[156:157], v142 offset:4704
	ds_read_b64_tr_b16 v[170:171], v142 offset:128
	ds_read_b64_tr_b16 v[172:173], v142 offset:4736
	ds_read_b64_tr_b16 v[178:179], v142 offset:160
	ds_read_b64_tr_b16 v[180:181], v142 offset:4768
	ds_read_b64_tr_b16 v[186:187], v142 offset:192
	ds_read_b64_tr_b16 v[188:189], v142 offset:4800
	ds_read_b64_tr_b16 v[198:199], v142 offset:224
	ds_read_b64_tr_b16 v[200:201], v142 offset:4832
	v_readlane_b32 s4, v255, 30
	v_cvt_pk_bf16_f32 v115, v87, v88
	v_add_f32_e32 v164, v102, v103
	v_add_u32_e32 v142, s4, v117
	v_mad_u64_u32 v[142:143], s[4:5], v142, s12, v[116:117]
	v_cvt_pk_bf16_f32 v102, v127, v128
	v_cvt_pk_bf16_f32 v103, v130, v131
	v_cvt_pk_bf16_f32 v105, v91, v92
	v_cvt_pk_bf16_f32 v107, v95, v96
	v_cvt_pk_bf16_f32 v92, v129, v132
	v_cvt_pk_bf16_f32 v95, v138, v139
	s_waitcnt lgkmcnt(0)
	v_mfma_f32_16x16x32_bf16 v[126:129], v[118:121], v[108:111], 0
	v_cvt_pk_bf16_f32 v104, v89, v90
	v_readlane_b32 s4, v255, 39
	v_cvt_pk_bf16_f32 v96, v97, v98
	v_mfma_f32_16x16x32_bf16 v[118:121], v[118:121], v[112:115], 0
	v_cvt_pk_bf16_f32 v97, v99, v158
	v_cvt_pk_bf16_f32 v98, v159, v211
	v_cvt_pk_bf16_f32 v99, v213, v214
	v_mfma_f32_16x16x32_bf16 v[130:133], v[122:125], v[108:111], 0
	v_cvt_pk_bf16_f32 v87, v146, v147
	v_cvt_pk_bf16_f32 v88, v215, v216
	v_cvt_pk_bf16_f32 v89, v217, v218
	v_mfma_f32_16x16x32_bf16 v[122:125], v[122:125], v[112:115], 0
	v_cvt_pk_bf16_f32 v90, v219, v220
	v_cvt_pk_bf16_f32 v91, v221, v222
	v_cvt_pk_bf16_f32 v80, v145, v153
	v_mfma_f32_16x16x32_bf16 v[138:141], v[134:137], v[108:111], 0
	v_cvt_pk_bf16_f32 v83, v83, v212
	v_cvt_pk_bf16_f32 v144, v223, v224
	v_cvt_pk_bf16_f32 v145, v225, v226
	v_mfma_f32_16x16x32_bf16 v[134:137], v[134:137], v[112:115], 0
	v_cvt_pk_bf16_f32 v146, v227, v228
	v_cvt_pk_bf16_f32 v147, v229, v230
	s_ashr_i32 s1, s0, 31
	v_mfma_f32_16x16x32_bf16 v[166:169], v[154:157], v[108:111], 0
	s_lshl_b64 s[0:1], s[0:1], 12
	v_ashrrev_i32_e32 v163, 31, v162
	s_mov_b32 s16, 0x800000
	v_mfma_f32_16x16x32_bf16 v[154:157], v[154:157], v[112:115], 0
	s_mov_b32 s11, s3
	s_mov_b32 s3, s15
	s_mov_b32 s17, 0x80000
	v_mfma_f32_16x16x32_bf16 v[174:177], v[170:173], v[108:111], 0
	s_mov_b32 s20, 0xa500000
	s_mov_b64 s[18:19], 0xa500800
	v_mfma_f32_16x16x32_bf16 v[170:173], v[170:173], v[112:115], 0
	v_mfma_f32_16x16x32_bf16 v[182:185], v[178:181], v[108:111], 0
	v_mfma_f32_16x16x32_bf16 v[178:181], v[178:181], v[112:115], 0
	v_mfma_f32_16x16x32_bf16 v[190:193], v[186:189], v[108:111], 0
	v_mfma_f32_16x16x32_bf16 v[186:189], v[186:189], v[112:115], 0
	v_mfma_f32_16x16x32_bf16 v[108:111], v[198:201], v[108:111], 0
	v_mfma_f32_16x16x32_bf16 v[112:115], v[198:201], v[112:115], 0
	ds_read_b64_tr_b16 v[200:201], v142 offset:4608
	ds_read_b64_tr_b16 v[198:199], v142
	ds_read_b64_tr_b16 v[202:203], v142 offset:32
	ds_read_b64_tr_b16 v[204:205], v142 offset:4640
	s_waitcnt lgkmcnt(2)
	v_mfma_f32_16x16x32_bf16 v[126:129], v[198:201], v[100:103], v[126:129]
	v_mfma_f32_16x16x32_bf16 v[118:121], v[198:201], v[104:107], v[118:121]
	ds_read_b64_tr_b16 v[198:199], v142 offset:64
	ds_read_b64_tr_b16 v[200:201], v142 offset:4672
	s_waitcnt lgkmcnt(0)
	v_mfma_f32_16x16x32_bf16 v[138:141], v[198:201], v[100:103], v[138:141]
	v_mfma_f32_16x16x32_bf16 v[134:137], v[198:201], v[104:107], v[134:137]
	ds_read_b64_tr_b16 v[198:199], v142 offset:96
	ds_read_b64_tr_b16 v[200:201], v142 offset:4704
	s_waitcnt lgkmcnt(0)
	v_mfma_f32_16x16x32_bf16 v[166:169], v[198:201], v[100:103], v[166:169]
	v_mfma_f32_16x16x32_bf16 v[154:157], v[198:201], v[104:107], v[154:157]
	ds_read_b64_tr_b16 v[198:199], v142 offset:128
	ds_read_b64_tr_b16 v[200:201], v142 offset:4736
	s_waitcnt lgkmcnt(0)
	v_mfma_f32_16x16x32_bf16 v[174:177], v[198:201], v[100:103], v[174:177]
	v_mfma_f32_16x16x32_bf16 v[170:173], v[198:201], v[104:107], v[170:173]
	ds_read_b64_tr_b16 v[198:199], v142 offset:160
	ds_read_b64_tr_b16 v[200:201], v142 offset:4768
	s_waitcnt lgkmcnt(0)
	v_mfma_f32_16x16x32_bf16 v[182:185], v[198:201], v[100:103], v[182:185]
	v_mfma_f32_16x16x32_bf16 v[178:181], v[198:201], v[104:107], v[178:181]
	ds_read_b64_tr_b16 v[198:199], v142 offset:192
	ds_read_b64_tr_b16 v[200:201], v142 offset:4800
	s_waitcnt lgkmcnt(0)
	v_mfma_f32_16x16x32_bf16 v[190:193], v[198:201], v[100:103], v[190:193]
	v_mfma_f32_16x16x32_bf16 v[186:189], v[198:201], v[104:107], v[186:189]
	ds_read_b64_tr_b16 v[198:199], v142 offset:224
	ds_read_b64_tr_b16 v[200:201], v142 offset:4832
	v_mfma_f32_16x16x32_bf16 v[130:133], v[202:205], v[100:103], v[130:133]
	s_waitcnt lgkmcnt(0)
; #define LAS __attribute__((address_space(3)))
; __device__ __forceinline__ f32x4 mfma16(bf16x8 a, bf16x8 b, f32x4 c) { return __builtin_amdgcn_mfma_f32_16x16x32_bf16(a, b, c, 0, 0, 0); }
; __device__ __forceinline__ s16x4 vtr(const LAS unsigned char* p) { return __builtin_bit_cast(s16x4, __builtin_amdgcn_ds_read_tr16_b64_v4i16((LAS s16x4*)p)); }
; __device__ __forceinline__ void attn_units(const Params& p, LAS unsigned char* buf, int sel, int wave) {
;     ...
; #pragma unroll
;         for (int kk = 0; kk < 5; ++kk) {
; #pragma unroll
;             for (int d = 0; d < 8; ++d) { const LAS unsigned char* ap = buf + (32 * wave + 32 * kk + 4 * g + (fr >> 2)) * 288 + (16 * d + 4 * (fr & 3)) * 2;
;                 const bf16x8 vf = cat8(vtr(ap), vtr(ap + 16 * 288));
;                 oacc[d][0] = mfma16(vf, pf[kk][0], oacc[d][0]); oacc[d][1] = mfma16(vf, pf[kk][1], oacc[d][1]); }
	v_mfma_f32_16x16x32_bf16 v[100:103], v[198:201], v[100:103], v[108:111]
	s_nop 2
	v_add_u32_e32 v108, s4, v117
	v_mad_u64_u32 v[142:143], s[4:5], v108, s12, v[116:117]
	v_mfma_f32_16x16x32_bf16 v[122:125], v[202:205], v[104:107], v[122:125]
	v_readlane_b32 s4, v255, 37
	v_mfma_f32_16x16x32_bf16 v[104:107], v[198:201], v[104:107], v[112:115]
	ds_read_b64_tr_b16 v[110:111], v142 offset:4608
	ds_read_b64_tr_b16 v[108:109], v142
	s_nop 0
	ds_read_b64_tr_b16 v[112:113], v142 offset:32
	ds_read_b64_tr_b16 v[114:115], v142 offset:4640
	s_waitcnt lgkmcnt(2)
	v_mfma_f32_16x16x32_bf16 v[126:129], v[108:111], v[92:95], v[126:129]
	v_mfma_f32_16x16x32_bf16 v[108:111], v[108:111], v[96:99], v[118:121]
	s_waitcnt lgkmcnt(0)
	v_mfma_f32_16x16x32_bf16 v[118:121], v[112:115], v[92:95], v[130:133]
	v_mfma_f32_16x16x32_bf16 v[112:115], v[112:115], v[96:99], v[122:125]
	s_nop 2
	ds_read_b64_tr_b16 v[122:123], v142 offset:64
	ds_read_b64_tr_b16 v[124:125], v142 offset:4672
	s_waitcnt lgkmcnt(0)
	v_mfma_f32_16x16x32_bf16 v[130:133], v[122:125], v[92:95], v[138:141]
	v_mfma_f32_16x16x32_bf16 v[122:125], v[122:125], v[96:99], v[134:137]
	s_nop 2
	ds_read_b64_tr_b16 v[134:135], v142 offset:96
	ds_read_b64_tr_b16 v[136:137], v142 offset:4704
	s_waitcnt lgkmcnt(0)
	v_mfma_f32_16x16x32_bf16 v[138:141], v[134:137], v[92:95], v[166:169]
	v_mfma_f32_16x16x32_bf16 v[134:137], v[134:137], v[96:99], v[154:157]
	s_nop 2
	ds_read_b64_tr_b16 v[154:155], v142 offset:128
	ds_read_b64_tr_b16 v[156:157], v142 offset:4736
	s_waitcnt lgkmcnt(0)
	v_mfma_f32_16x16x32_bf16 v[166:169], v[154:157], v[92:95], v[174:177]
	v_mfma_f32_16x16x32_bf16 v[154:157], v[154:157], v[96:99], v[170:173]
	s_nop 2
	ds_read_b64_tr_b16 v[170:171], v142 offset:160
	ds_read_b64_tr_b16 v[172:173], v142 offset:4768
	s_waitcnt lgkmcnt(0)
	v_mfma_f32_16x16x32_bf16 v[174:177], v[170:173], v[92:95], v[182:185]
	v_mfma_f32_16x16x32_bf16 v[170:173], v[170:173], v[96:99], v[178:181]
	s_nop 2
	ds_read_b64_tr_b16 v[178:179], v142 offset:192
	ds_read_b64_tr_b16 v[180:181], v142 offset:4800
	s_waitcnt lgkmcnt(0)
	v_mfma_f32_16x16x32_bf16 v[182:185], v[178:181], v[92:95], v[190:193]
	v_mfma_f32_16x16x32_bf16 v[178:181], v[178:181], v[96:99], v[186:189]
	s_nop 2
	ds_read_b64_tr_b16 v[186:187], v142 offset:224
	ds_read_b64_tr_b16 v[188:189], v142 offset:4832
	s_waitcnt lgkmcnt(0)
	v_mfma_f32_16x16x32_bf16 v[92:95], v[186:189], v[92:95], v[100:103]
	s_nop 2
	v_add_u32_e32 v100, s4, v117
	v_mad_u64_u32 v[142:143], s[4:5], v100, s12, v[116:117]
	v_mfma_f32_16x16x32_bf16 v[96:99], v[186:189], v[96:99], v[104:107]
	ds_read_b64_tr_b16 v[102:103], v142 offset:4608
	ds_read_b64_tr_b16 v[100:101], v142
	s_nop 0
	ds_read_b64_tr_b16 v[104:105], v142 offset:32
	ds_read_b64_tr_b16 v[106:107], v142 offset:4640
	v_readlane_b32 s4, v255, 38
	s_waitcnt lgkmcnt(2)
	v_mfma_f32_16x16x32_bf16 v[126:129], v[100:103], v[84:87], v[126:129]
	v_mfma_f32_16x16x32_bf16 v[100:103], v[100:103], v[88:91], v[108:111]
	s_nop 2
	ds_read_b64_tr_b16 v[108:109], v142 offset:64
	ds_read_b64_tr_b16 v[110:111], v142 offset:4672
	s_waitcnt lgkmcnt(2)
	v_mfma_f32_16x16x32_bf16 v[118:121], v[104:107], v[84:87], v[118:121]
	v_mfma_f32_16x16x32_bf16 v[104:107], v[104:107], v[88:91], v[112:115]
	s_waitcnt lgkmcnt(0)
	v_mfma_f32_16x16x32_bf16 v[112:115], v[108:111], v[84:87], v[130:133]
	v_mfma_f32_16x16x32_bf16 v[122:125], v[108:111], v[88:91], v[122:125]
	ds_read_b64_tr_b16 v[108:109], v142 offset:96
	ds_read_b64_tr_b16 v[110:111], v142 offset:4704
	s_waitcnt lgkmcnt(0)
	v_mfma_f32_16x16x32_bf16 v[186:189], v[108:111], v[84:87], v[138:141]
	v_mfma_f32_16x16x32_bf16 v[190:193], v[108:111], v[88:91], v[134:137]
	ds_read_b64_tr_b16 v[108:109], v142 offset:128
	ds_read_b64_tr_b16 v[110:111], v142 offset:4736
	s_waitcnt lgkmcnt(0)
	v_mfma_f32_16x16x32_bf16 v[166:169], v[108:111], v[84:87], v[166:169]
	v_mfma_f32_16x16x32_bf16 v[154:157], v[108:111], v[88:91], v[154:157]
	ds_read_b64_tr_b16 v[108:109], v142 offset:160
	ds_read_b64_tr_b16 v[110:111], v142 offset:4768
	s_waitcnt lgkmcnt(0)
	v_mfma_f32_16x16x32_bf16 v[174:177], v[108:111], v[84:87], v[174:177]
	v_mfma_f32_16x16x32_bf16 v[170:173], v[108:111], v[88:91], v[170:173]
	ds_read_b64_tr_b16 v[108:109], v142 offset:192
	ds_read_b64_tr_b16 v[110:111], v142 offset:4800
	s_waitcnt lgkmcnt(0)
	v_mfma_f32_16x16x32_bf16 v[182:185], v[108:111], v[84:87], v[182:185]
	v_mfma_f32_16x16x32_bf16 v[178:181], v[108:111], v[88:91], v[178:181]
	ds_read_b64_tr_b16 v[108:109], v142 offset:224
	ds_read_b64_tr_b16 v[110:111], v142 offset:4832
	s_waitcnt lgkmcnt(0)
	v_mfma_f32_16x16x32_bf16 v[198:201], v[108:111], v[84:87], v[92:95]
	v_add_u32_e32 v84, s4, v117
	v_mad_u64_u32 v[158:159], s[4:5], v84, s12, v[116:117]
	v_mfma_f32_16x16x32_bf16 v[202:205], v[108:111], v[88:91], v[96:99]
	ds_read_b64_tr_b16 v[86:87], v158 offset:4608
	ds_read_b64_tr_b16 v[84:85], v158
	ds_read_b64_tr_b16 v[88:89], v158 offset:32
	ds_read_b64_tr_b16 v[90:91], v158 offset:4640
	v_readlane_b32 s4, v255, 48
	s_waitcnt lgkmcnt(2)
	v_mfma_f32_16x16x32_bf16 v[140:143], v[84:87], v[80:83], v[126:129]
	v_readlane_b32 s5, v255, 49
	s_add_u32 s0, s4, s0
	s_addc_u32 s1, s5, s1
	v_mfma_f32_16x16x32_bf16 v[108:111], v[84:87], v[144:147], v[100:103]
	ds_read_b64_tr_b16 v[84:85], v158 offset:64
	ds_read_b64_tr_b16 v[86:87], v158 offset:4672
	s_lshl_b32 s4, s2, 7
	s_mov_b32 s5, s15
	s_waitcnt lgkmcnt(0)
	v_mfma_f32_16x16x32_bf16 v[132:135], v[84:87], v[80:83], v[112:115]
	v_readlane_b32 s12, v255, 44
	v_readlane_b32 s13, v255, 45
	v_mfma_f32_16x16x32_bf16 v[100:103], v[84:87], v[144:147], v[122:125]
	ds_read_b64_tr_b16 v[84:85], v158 offset:96
	ds_read_b64_tr_b16 v[86:87], v158 offset:4704
	s_waitcnt lgkmcnt(0)
; #define LAS __attribute__((address_space(3)))
; __device__ __forceinline__ void attn_units(const Params& p, LAS unsigned char* buf, int sel, int wave) {
;     ...
;         for (int kk = 0; kk < 5; ++kk) {
; #pragma unroll
;             for (int d = 0; d < 8; ++d) { const LAS unsigned char* ap = buf + (32 * wave + 32 * kk + 4 * g + (fr >> 2)) * 288 + (16 * d + 4 * (fr & 3)) * 2;
;                 const bf16x8 vf = cat8(vtr(ap), vtr(ap + 16 * 288));
;                 oacc[d][0] = mfma16(vf, pf[kk][0], oacc[d][0]); oacc[d][1] = mfma16(vf, pf[kk][1], oacc[d][1]); }
;         }
; #pragma unroll
;         for (int qt = 0; qt < 2; ++qt) {
;             const size_t m = rb + (size_t)(i0 + 16 * qt + fr) * r + rho;
;             const float inv = 1.0f / lq[qt], lse = mq[qt] + log2f(lq[qt]);
;             if (sel == 0) {
;                 if (g == 0) LSE[(size_t)slot * MTOK * 8 + m * 8 + h] = lse;
; #pragma unroll
;                 for (int d = 0; d < 8; ++d) { const f32x4 o = oacc[d][qt] * inv; u32x2 w; w.x = cvtpk(o[0], o[1]); w.y = cvtpk(o[2], o[3]);
;                     *(u32x2*)(OBR + (size_t)slot * MTOK * 1024 + m * 1024 + h * 128 + 16 * d + 4 * g) = w; }
;             } else {
;                 const float l0 = LSE[m * 8 + h], l1 = LSE[(size_t)MTOK * 8 + m * 8 + h];
;                 const float M = fmaxf(fmaxf(l0, l1), lse);
;                 const float w0 = __builtin_amdgcn_exp2f(l0 - M), w1 = __builtin_amdgcn_exp2f(l1 - M), w2 = __builtin_amdgcn_exp2f(lse - M);
;                 const float wi = 1.0f / (w0 + w1 + w2), a0 = w0 * wi, a1 = w1 * wi, a2 = w2 * wi * inv;
; #pragma unroll
;                 for (int d = 0; d < 8; ++d) { const size_t off = m * 1024 + h * 128 + 16 * d + 4 * g;
;                     const u32x2 x0 = *(const u32x2*)(OBR + off), x1 = *(const u32x2*)(OBR + (size_t)MTOK * 1024 + off);
;                     const f32x4 o = oacc[d][qt];
;                     const float r0 = a0 * bflo(x0.x) + a1 * bflo(x1.x) + a2 * o[0], r1 = a0 * bfhi(x0.x) + a1 * bfhi(x1.x) + a2 * o[1];
;                     const float r2 = a0 * bflo(x0.y) + a1 * bflo(x1.y) + a2 * o[2], r3 = a0 * bfhi(x0.y) + a1 * bfhi(x1.y) + a2 * o[3];
;                     u32x2 w; w.x = cvtpk(r0, r1); w.y = cvtpk(r2, r3);
;                     *(u32x2*)(OA + m * DM + 1024 + h * 128 + 16 * d + 4 * g) = w; }
	v_mfma_f32_16x16x32_bf16 v[128:131], v[84:87], v[80:83], v[186:189]
	v_mfma_f32_16x16x32_bf16 v[96:99], v[84:87], v[144:147], v[190:193]
	ds_read_b64_tr_b16 v[84:85], v158 offset:128
	ds_read_b64_tr_b16 v[86:87], v158 offset:4736
	s_waitcnt lgkmcnt(0)
	v_mfma_f32_16x16x32_bf16 v[124:127], v[84:87], v[80:83], v[166:169]
	v_mfma_f32_16x16x32_bf16 v[92:95], v[84:87], v[144:147], v[154:157]
	ds_read_b64_tr_b16 v[84:85], v158 offset:160
	ds_read_b64_tr_b16 v[86:87], v158 offset:4768
	v_mfma_f32_16x16x32_bf16 v[136:139], v[88:91], v[80:83], v[118:121]
	v_mfma_f32_16x16x32_bf16 v[104:107], v[88:91], v[144:147], v[104:107]
	s_waitcnt lgkmcnt(0)
	v_mfma_f32_16x16x32_bf16 v[120:123], v[84:87], v[80:83], v[174:177]
	v_mfma_f32_16x16x32_bf16 v[88:91], v[84:87], v[144:147], v[170:173]
	ds_read_b64_tr_b16 v[84:85], v158 offset:192
	ds_read_b64_tr_b16 v[86:87], v158 offset:4800
	ds_read_b64_tr_b16 v[154:155], v158 offset:224
	ds_read_b64_tr_b16 v[156:157], v158 offset:4832
	s_waitcnt lgkmcnt(2)
	v_mfma_f32_16x16x32_bf16 v[116:119], v[84:87], v[80:83], v[182:185]
	v_mfma_f32_16x16x32_bf16 v[84:87], v[84:87], v[144:147], v[178:181]
	s_waitcnt lgkmcnt(0)
	v_mfma_f32_16x16x32_bf16 v[112:115], v[154:157], v[80:83], v[198:201]
	v_mfma_f32_16x16x32_bf16 v[80:83], v[154:157], v[144:147], v[202:205]
	v_lshl_add_u64 v[144:145], v[162:163], 0, s[4:5]
	v_div_scale_f32 v153, s[4:5], v152, v152, 1.0
	v_rcp_f32_e32 v154, v153
	v_lshl_add_u64 v[146:147], v[160:161], 4, s[0:1]
	s_lshl_b64 s[4:5], s[2:3], 2
	s_lshl_b32 s2, s2, 8
	v_fma_f32 v155, -v153, v154, 1.0
	v_fmac_f32_e32 v154, v155, v154
	v_div_scale_f32 v155, vcc, 1.0, v152, 1.0
	v_mul_f32_e32 v156, v155, v154
	v_fma_f32 v157, -v153, v156, v155
	v_fmac_f32_e32 v156, v157, v154
	v_fma_f32 v153, -v153, v156, v155
	v_div_fmas_f32 v153, v153, v154, v156
	v_cmp_gt_f32_e32 vcc, s16, v152
	v_div_fixup_f32 v154, v153, v152, 1.0
	s_nop 0
	v_cndmask_b32_e64 v153, 0, 32, vcc
	v_ldexp_f32 v152, v152, v153
	v_log_f32_e32 v152, v152
	v_cndmask_b32_e32 v153, 0, v196, vcc
	v_sub_f32_e32 v152, v152, v153
	v_add_f32_e32 v150, v150, v152
	v_lshlrev_b64 v[152:153], 5, v[146:147]
	v_lshl_add_u64 v[152:153], s[12:13], 0, v[152:153]
	v_lshl_add_u64 v[152:153], v[152:153], 0, s[4:5]
	global_load_dword v155, v[152:153], off
	v_add_co_u32_e32 v152, vcc, s17, v152
	s_nop 1
	v_addc_co_u32_e32 v153, vcc, 0, v153, vcc
	global_load_dword v152, v[152:153], off
	s_waitcnt vmcnt(0)
	v_max3_f32 v153, v155, v152, v150
	v_sub_f32_e32 v155, v155, v153
	v_sub_f32_e32 v152, v152, v153
	v_exp_f32_e32 v159, v155
	v_exp_f32_e32 v158, v152
	v_sub_f32_e32 v150, v150, v153
	v_exp_f32_e32 v150, v150
	v_add_f32_e32 v152, v159, v158
	v_add_f32_e32 v152, v150, v152
	v_div_scale_f32 v153, s[8:9], v152, v152, 1.0
	v_rcp_f32_e32 v155, v153
	v_readlane_b32 s8, v255, 40
	v_readlane_b32 s9, v255, 41
	v_fma_f32 v156, -v153, v155, 1.0
	v_fmac_f32_e32 v155, v156, v155
	v_div_scale_f32 v156, vcc, 1.0, v152, 1.0
	v_mul_f32_e32 v157, v156, v155
	v_fma_f32 v160, -v153, v157, v156
	v_fmac_f32_e32 v157, v160, v155
	v_fma_f32 v153, -v153, v157, v156
	v_div_fmas_f32 v153, v153, v155, v157
	v_div_fixup_f32 v160, v153, v152, 1.0
	v_mul_f32_e32 v150, v150, v160
	v_lshlrev_b64 v[152:153], 10, v[146:147]
	v_mul_f32_e32 v150, v154, v150
	v_lshl_add_u64 v[154:155], v[152:153], 0, v[144:145]
	v_lshlrev_b64 v[156:157], 1, v[154:155]
	v_lshl_add_u64 v[154:155], s[68:69], 0, v[156:157]
	v_lshl_add_u64 v[156:157], s[8:9], 0, v[156:157]
	global_load_dwordx2 v[166:167], v[154:155], off
	global_load_dwordx2 v[168:169], v[156:157], off
	global_load_dwordx2 v[198:199], v[154:155], off offset:32
	global_load_dwordx2 v[200:201], v[156:157], off offset:32
	global_load_dwordx2 v[202:203], v[154:155], off offset:64
	global_load_dwordx2 v[204:205], v[156:157], off offset:64
	global_load_dwordx2 v[206:207], v[154:155], off offset:96
	global_load_dwordx2 v[208:209], v[156:157], off offset:96
	global_load_dwordx2 v[210:211], v[154:155], off offset:128
	global_load_dwordx2 v[212:213], v[156:157], off offset:128
	global_load_dwordx2 v[214:215], v[154:155], off offset:160
	global_load_dwordx2 v[216:217], v[156:157], off offset:160
	global_load_dwordx2 v[218:219], v[154:155], off offset:192
	global_load_dwordx2 v[220:221], v[156:157], off offset:192
	global_load_dwordx2 v[222:223], v[154:155], off offset:224
	global_load_dwordx2 v[224:225], v[156:157], off offset:224
	v_pk_mul_f32 v[158:159], v[158:159], v[160:161] op_sel_hi:[1,0]
	v_lshlrev_b64 v[146:147], 12, v[146:147]
	v_lshl_add_u64 v[146:147], s[68:69], 0, v[146:147]
	v_lshl_add_u64 v[152:153], v[146:147], 0, s[2:3]
	v_lshlrev_b64 v[146:147], 1, v[162:163]
	v_lshl_add_u64 v[162:163], v[152:153], 0, v[146:147]
	v_lshl_add_u64 v[152:153], v[162:163], 0, s[18:19]
	s_waitcnt vmcnt(15)
	v_lshlrev_b32_e32 v172, 16, v166
	s_waitcnt vmcnt(14)
	v_and_b32_e32 v173, 0xffff0000, v168
	v_lshlrev_b32_e32 v170, 16, v168
	v_and_b32_e32 v171, 0xffff0000, v166
	v_pk_mul_f32 v[172:173], v[158:159], v[172:173] op_sel:[1,0] op_sel_hi:[0,1]
	v_pk_fma_f32 v[170:171], v[158:159], v[170:171], v[172:173]
	v_lshlrev_b32_e32 v166, 16, v167
	v_pk_fma_f32 v[140:141], v[140:141], v[150:151], v[170:171] op_sel_hi:[1,0,1]
	v_and_b32_e32 v171, 0xffff0000, v167
	v_and_b32_e32 v167, 0xffff0000, v169
	v_lshlrev_b32_e32 v170, 16, v169
	v_pk_mul_f32 v[166:167], v[158:159], v[166:167] op_sel:[1,0] op_sel_hi:[0,1]
	v_pk_fma_f32 v[166:167], v[158:159], v[170:171], v[166:167]
	v_cvt_pk_bf16_f32 v140, v140, v141
	v_pk_fma_f32 v[142:143], v[142:143], v[150:151], v[166:167] op_sel_hi:[1,0,1]
	s_nop 0
	v_cvt_pk_bf16_f32 v141, v142, v143
	v_add_co_u32_e32 v142, vcc, s20, v162
	s_nop 1
	v_addc_co_u32_e32 v143, vcc, 0, v163, vcc
	global_store_dwordx2 v[142:143], v[140:141], off offset:2048
	s_waitcnt vmcnt(13)
; __device__ __forceinline__ unsigned cvtpk(float lo, float hi) { f32x2 v = {lo, hi}; bf16x2_t b = __builtin_convertvector(v, bf16x2_t); return __builtin_bit_cast(unsigned, b); }
; __device__ __forceinline__ void attn_units(const Params& p, LAS unsigned char* buf, int sel, int wave) {
;     ...
; #pragma unroll
;                 for (int d = 0; d < 8; ++d) { const size_t off = m * 1024 + h * 128 + 16 * d + 4 * g;
;                     const u32x2 x0 = *(const u32x2*)(OBR + off), x1 = *(const u32x2*)(OBR + (size_t)MTOK * 1024 + off);
;                     const f32x4 o = oacc[d][qt];
;                     const float r0 = a0 * bflo(x0.x) + a1 * bflo(x1.x) + a2 * o[0], r1 = a0 * bfhi(x0.x) + a1 * bfhi(x1.x) + a2 * o[1];
;                     const float r2 = a0 * bflo(x0.y) + a1 * bflo(x1.y) + a2 * o[2], r3 = a0 * bfhi(x0.y) + a1 * bfhi(x1.y) + a2 * o[3];
;                     u32x2 w; w.x = cvtpk(r0, r1); w.y = cvtpk(r2, r3);
;                     *(u32x2*)(OA + m * DM + 1024 + h * 128 + 16 * d + 4 * g) = w; }
	s_nop 0
	v_mov_b32_e32 v140, v198
	v_mov_b32_e32 v141, v199
	s_nop 0
	v_mov_b32_e32 v142, v200
	v_mov_b32_e32 v143, v201
	v_lshlrev_b32_e32 v166, 16, v140
	v_and_b32_e32 v167, 0xffff0000, v142
	v_lshlrev_b32_e32 v162, 16, v142
	v_and_b32_e32 v163, 0xffff0000, v140
	v_pk_mul_f32 v[166:167], v[158:159], v[166:167] op_sel:[1,0] op_sel_hi:[0,1]
	v_pk_fma_f32 v[162:163], v[158:159], v[162:163], v[166:167]
	v_lshlrev_b32_e32 v140, 16, v141
	v_pk_fma_f32 v[136:137], v[136:137], v[150:151], v[162:163] op_sel_hi:[1,0,1]
	v_and_b32_e32 v163, 0xffff0000, v141
	v_and_b32_e32 v141, 0xffff0000, v143
	v_lshlrev_b32_e32 v162, 16, v143
	v_pk_mul_f32 v[140:141], v[158:159], v[140:141] op_sel:[1,0] op_sel_hi:[0,1]
	v_pk_fma_f32 v[140:141], v[158:159], v[162:163], v[140:141]
	v_cvt_pk_bf16_f32 v136, v136, v137
	v_pk_fma_f32 v[138:139], v[138:139], v[150:151], v[140:141] op_sel_hi:[1,0,1]
	s_nop 0
	v_cvt_pk_bf16_f32 v137, v138, v139
	global_store_dwordx2 v[152:153], v[136:137], off offset:32
	s_waitcnt vmcnt(12)
	s_nop 0
	v_mov_b32_e32 v136, v202
	v_mov_b32_e32 v137, v203
	s_nop 0
	v_mov_b32_e32 v138, v204
	v_mov_b32_e32 v139, v205
	v_lshlrev_b32_e32 v142, 16, v136
	v_and_b32_e32 v143, 0xffff0000, v138
	v_lshlrev_b32_e32 v140, 16, v138
	v_and_b32_e32 v141, 0xffff0000, v136
	v_pk_mul_f32 v[142:143], v[158:159], v[142:143] op_sel:[1,0] op_sel_hi:[0,1]
	v_pk_fma_f32 v[140:141], v[158:159], v[140:141], v[142:143]
	v_lshlrev_b32_e32 v136, 16, v137
	v_pk_fma_f32 v[132:133], v[132:133], v[150:151], v[140:141] op_sel_hi:[1,0,1]
	v_and_b32_e32 v141, 0xffff0000, v137
	v_and_b32_e32 v137, 0xffff0000, v139
	v_lshlrev_b32_e32 v140, 16, v139
	v_pk_mul_f32 v[136:137], v[158:159], v[136:137] op_sel:[1,0] op_sel_hi:[0,1]
	v_pk_fma_f32 v[136:137], v[158:159], v[140:141], v[136:137]
	v_cvt_pk_bf16_f32 v132, v132, v133
	v_pk_fma_f32 v[134:135], v[134:135], v[150:151], v[136:137] op_sel_hi:[1,0,1]
	s_nop 0
	v_cvt_pk_bf16_f32 v133, v134, v135
	global_store_dwordx2 v[152:153], v[132:133], off offset:64
	s_waitcnt vmcnt(11)
	s_nop 0
	v_mov_b32_e32 v132, v206
	v_mov_b32_e32 v133, v207
	s_nop 0
	v_mov_b32_e32 v134, v208
	v_mov_b32_e32 v135, v209
	v_lshlrev_b32_e32 v138, 16, v132
	v_and_b32_e32 v139, 0xffff0000, v134
	v_lshlrev_b32_e32 v136, 16, v134
	v_and_b32_e32 v137, 0xffff0000, v132
	v_pk_mul_f32 v[138:139], v[158:159], v[138:139] op_sel:[1,0] op_sel_hi:[0,1]
	v_pk_fma_f32 v[136:137], v[158:159], v[136:137], v[138:139]
	v_lshlrev_b32_e32 v132, 16, v133
	v_pk_fma_f32 v[128:129], v[128:129], v[150:151], v[136:137] op_sel_hi:[1,0,1]
	v_and_b32_e32 v137, 0xffff0000, v133
	v_and_b32_e32 v133, 0xffff0000, v135
	v_lshlrev_b32_e32 v136, 16, v135
	v_pk_mul_f32 v[132:133], v[158:159], v[132:133] op_sel:[1,0] op_sel_hi:[0,1]
	v_pk_fma_f32 v[132:133], v[158:159], v[136:137], v[132:133]
	v_cvt_pk_bf16_f32 v128, v128, v129
	v_pk_fma_f32 v[130:131], v[130:131], v[150:151], v[132:133] op_sel_hi:[1,0,1]
	s_nop 0
	v_cvt_pk_bf16_f32 v129, v130, v131
	global_store_dwordx2 v[152:153], v[128:129], off offset:96
	s_waitcnt vmcnt(10)
	s_nop 0
	v_mov_b32_e32 v128, v210
	v_mov_b32_e32 v129, v211
	s_nop 0
	v_mov_b32_e32 v130, v212
	v_mov_b32_e32 v131, v213
	v_lshlrev_b32_e32 v134, 16, v128
	v_and_b32_e32 v135, 0xffff0000, v130
	v_lshlrev_b32_e32 v132, 16, v130
	v_and_b32_e32 v133, 0xffff0000, v128
	v_pk_mul_f32 v[134:135], v[158:159], v[134:135] op_sel:[1,0] op_sel_hi:[0,1]
	v_pk_fma_f32 v[132:133], v[158:159], v[132:133], v[134:135]
	v_lshlrev_b32_e32 v128, 16, v129
	v_pk_fma_f32 v[124:125], v[124:125], v[150:151], v[132:133] op_sel_hi:[1,0,1]
	v_and_b32_e32 v133, 0xffff0000, v129
	v_and_b32_e32 v129, 0xffff0000, v131
	v_lshlrev_b32_e32 v132, 16, v131
	v_pk_mul_f32 v[128:129], v[158:159], v[128:129] op_sel:[1,0] op_sel_hi:[0,1]
	v_pk_fma_f32 v[128:129], v[158:159], v[132:133], v[128:129]
	v_cvt_pk_bf16_f32 v124, v124, v125
	v_pk_fma_f32 v[126:127], v[126:127], v[150:151], v[128:129] op_sel_hi:[1,0,1]
	s_nop 0
	v_cvt_pk_bf16_f32 v125, v126, v127
	global_store_dwordx2 v[152:153], v[124:125], off offset:128
	s_waitcnt vmcnt(9)
	s_nop 0
	v_mov_b32_e32 v124, v214
	v_mov_b32_e32 v125, v215
	s_nop 0
	v_mov_b32_e32 v126, v216
	v_mov_b32_e32 v127, v217
	v_lshlrev_b32_e32 v130, 16, v124
	v_and_b32_e32 v131, 0xffff0000, v126
	v_lshlrev_b32_e32 v128, 16, v126
	v_and_b32_e32 v129, 0xffff0000, v124
	v_pk_mul_f32 v[130:131], v[158:159], v[130:131] op_sel:[1,0] op_sel_hi:[0,1]
	v_pk_fma_f32 v[128:129], v[158:159], v[128:129], v[130:131]
	v_lshlrev_b32_e32 v124, 16, v125
	v_pk_fma_f32 v[120:121], v[120:121], v[150:151], v[128:129] op_sel_hi:[1,0,1]
	v_and_b32_e32 v129, 0xffff0000, v125
	v_and_b32_e32 v125, 0xffff0000, v127
	v_lshlrev_b32_e32 v128, 16, v127
	v_pk_mul_f32 v[124:125], v[158:159], v[124:125] op_sel:[1,0] op_sel_hi:[0,1]
	v_pk_fma_f32 v[124:125], v[158:159], v[128:129], v[124:125]
	v_cvt_pk_bf16_f32 v120, v120, v121
	v_pk_fma_f32 v[122:123], v[122:123], v[150:151], v[124:125] op_sel_hi:[1,0,1]
	s_nop 0
	v_cvt_pk_bf16_f32 v121, v122, v123
	global_store_dwordx2 v[152:153], v[120:121], off offset:160
	s_waitcnt vmcnt(8)
	s_nop 0
	v_mov_b32_e32 v120, v218
	v_mov_b32_e32 v121, v219
	s_nop 0
	v_mov_b32_e32 v122, v220
	v_mov_b32_e32 v123, v221
	v_lshlrev_b32_e32 v126, 16, v120
	v_and_b32_e32 v127, 0xffff0000, v122
	v_lshlrev_b32_e32 v124, 16, v122
	v_and_b32_e32 v125, 0xffff0000, v120
	v_pk_mul_f32 v[126:127], v[158:159], v[126:127] op_sel:[1,0] op_sel_hi:[0,1]
	v_pk_fma_f32 v[124:125], v[158:159], v[124:125], v[126:127]
	v_lshlrev_b32_e32 v120, 16, v121
	v_pk_fma_f32 v[116:117], v[116:117], v[150:151], v[124:125] op_sel_hi:[1,0,1]
	v_and_b32_e32 v125, 0xffff0000, v121
	v_and_b32_e32 v121, 0xffff0000, v123
	v_lshlrev_b32_e32 v124, 16, v123
	v_pk_mul_f32 v[120:121], v[158:159], v[120:121] op_sel:[1,0] op_sel_hi:[0,1]
	v_pk_fma_f32 v[120:121], v[158:159], v[124:125], v[120:121]
	v_cvt_pk_bf16_f32 v116, v116, v117
	v_pk_fma_f32 v[118:119], v[118:119], v[150:151], v[120:121] op_sel_hi:[1,0,1]
	s_nop 0
	v_cvt_pk_bf16_f32 v117, v118, v119
	global_store_dwordx2 v[152:153], v[116:117], off offset:192
	s_waitcnt vmcnt(7)
; __device__ __forceinline__ unsigned cvtpk(float lo, float hi) { f32x2 v = {lo, hi}; bf16x2_t b = __builtin_convertvector(v, bf16x2_t); return __builtin_bit_cast(unsigned, b); }
; __device__ __forceinline__ void attn_units(const Params& p, LAS unsigned char* buf, int sel, int wave) {
;     ...
;         for (int qt = 0; qt < 2; ++qt) {
;             const size_t m = rb + (size_t)(i0 + 16 * qt + fr) * r + rho;
;             const float inv = 1.0f / lq[qt], lse = mq[qt] + log2f(lq[qt]);
;             if (sel == 0) {
;                 if (g == 0) LSE[(size_t)slot * MTOK * 8 + m * 8 + h] = lse;
; #pragma unroll
;                 for (int d = 0; d < 8; ++d) { const f32x4 o = oacc[d][qt] * inv; u32x2 w; w.x = cvtpk(o[0], o[1]); w.y = cvtpk(o[2], o[3]);
;                     *(u32x2*)(OBR + (size_t)slot * MTOK * 1024 + m * 1024 + h * 128 + 16 * d + 4 * g) = w; }
;             } else {
;                 const float l0 = LSE[m * 8 + h], l1 = LSE[(size_t)MTOK * 8 + m * 8 + h];
;                 const float M = fmaxf(fmaxf(l0, l1), lse);
;                 const float w0 = __builtin_amdgcn_exp2f(l0 - M), w1 = __builtin_amdgcn_exp2f(l1 - M), w2 = __builtin_amdgcn_exp2f(lse - M);
;                 const float wi = 1.0f / (w0 + w1 + w2), a0 = w0 * wi, a1 = w1 * wi, a2 = w2 * wi * inv;
; #pragma unroll
;                 for (int d = 0; d < 8; ++d) { const size_t off = m * 1024 + h * 128 + 16 * d + 4 * g;
;                     const u32x2 x0 = *(const u32x2*)(OBR + off), x1 = *(const u32x2*)(OBR + (size_t)MTOK * 1024 + off);
;                     const f32x4 o = oacc[d][qt];
;                     const float r0 = a0 * bflo(x0.x) + a1 * bflo(x1.x) + a2 * o[0], r1 = a0 * bfhi(x0.x) + a1 * bfhi(x1.x) + a2 * o[1];
;                     const float r2 = a0 * bflo(x0.y) + a1 * bflo(x1.y) + a2 * o[2], r3 = a0 * bfhi(x0.y) + a1 * bfhi(x1.y) + a2 * o[3];
;                     u32x2 w; w.x = cvtpk(r0, r1); w.y = cvtpk(r2, r3);
;                     *(u32x2*)(OA + m * DM + 1024 + h * 128 + 16 * d + 4 * g) = w; }
	s_nop 0
	v_mov_b32_e32 v116, v222
	v_mov_b32_e32 v117, v223
	s_nop 0
	v_mov_b32_e32 v118, v224
	v_mov_b32_e32 v119, v225
	v_lshlrev_b32_e32 v122, 16, v116
	v_and_b32_e32 v123, 0xffff0000, v118
	v_lshlrev_b32_e32 v120, 16, v118
	v_and_b32_e32 v121, 0xffff0000, v116
	v_pk_mul_f32 v[122:123], v[158:159], v[122:123] op_sel:[1,0] op_sel_hi:[0,1]
	v_pk_fma_f32 v[120:121], v[158:159], v[120:121], v[122:123]
	v_lshlrev_b32_e32 v116, 16, v117
	v_pk_fma_f32 v[112:113], v[112:113], v[150:151], v[120:121] op_sel_hi:[1,0,1]
	v_and_b32_e32 v121, 0xffff0000, v117
	v_and_b32_e32 v117, 0xffff0000, v119
	v_lshlrev_b32_e32 v120, 16, v119
	v_pk_mul_f32 v[116:117], v[158:159], v[116:117] op_sel:[1,0] op_sel_hi:[0,1]
	v_pk_fma_f32 v[116:117], v[158:159], v[120:121], v[116:117]
	v_cvt_pk_bf16_f32 v112, v112, v113
	v_pk_fma_f32 v[114:115], v[114:115], v[150:151], v[116:117] op_sel_hi:[1,0,1]
	s_nop 0
	v_cvt_pk_bf16_f32 v113, v114, v115
	global_store_dwordx2 v[152:153], v[112:113], off offset:224
	v_lshl_add_u64 v[114:115], v[148:149], 4, s[0:1]
	v_div_scale_f32 v112, s[0:1], v164, v164, 1.0
	v_rcp_f32_e32 v113, v112
	s_nop 0
	v_fma_f32 v116, -v112, v113, 1.0
	v_fmac_f32_e32 v113, v116, v113
	v_div_scale_f32 v116, vcc, 1.0, v164, 1.0
	v_mul_f32_e32 v117, v116, v113
	v_fma_f32 v118, -v112, v117, v116
	v_fmac_f32_e32 v117, v118, v113
	v_fma_f32 v112, -v112, v117, v116
	v_div_fmas_f32 v112, v112, v113, v117
	v_cmp_gt_f32_e32 vcc, s16, v164
	v_div_fixup_f32 v116, v112, v164, 1.0
	s_nop 0
	v_cndmask_b32_e64 v112, 0, 32, vcc
	v_ldexp_f32 v112, v164, v112
	v_log_f32_e32 v112, v112
	v_cndmask_b32_e32 v113, 0, v196, vcc
	v_sub_f32_e32 v112, v112, v113
	v_add_f32_e32 v117, v151, v112
	v_lshlrev_b64 v[112:113], 5, v[114:115]
	v_lshl_add_u64 v[112:113], s[12:13], 0, v[112:113]
	v_lshl_add_u64 v[112:113], v[112:113], 0, s[4:5]
	global_load_dword v118, v[112:113], off
	v_add_co_u32_e32 v112, vcc, s17, v112
	s_nop 1
	v_addc_co_u32_e32 v113, vcc, 0, v113, vcc
	global_load_dword v112, v[112:113], off
	s_waitcnt vmcnt(0)
	v_max3_f32 v113, v118, v112, v117
	v_sub_f32_e32 v118, v118, v113
	v_sub_f32_e32 v112, v112, v113
	v_exp_f32_e32 v121, v118
	v_exp_f32_e32 v120, v112
	v_sub_f32_e32 v112, v117, v113
	v_exp_f32_e32 v112, v112
	v_add_f32_e32 v113, v121, v120
	v_add_f32_e32 v113, v112, v113
	v_div_scale_f32 v117, s[0:1], v113, v113, 1.0
	v_rcp_f32_e32 v118, v117
	v_readlane_b32 s0, v255, 50
	s_add_i32 s0, s0, s70
	s_cmp_eq_u32 s10, s21
	v_fma_f32 v119, -v117, v118, 1.0
	v_fmac_f32_e32 v118, v119, v118
	v_div_scale_f32 v119, vcc, 1.0, v113, 1.0
	v_mul_f32_e32 v122, v119, v118
	v_fma_f32 v123, -v117, v122, v119
	v_fmac_f32_e32 v122, v123, v118
	v_fma_f32 v117, -v117, v122, v119
	v_div_fmas_f32 v117, v117, v118, v122
	v_div_fixup_f32 v124, v117, v113, 1.0
	v_mul_f32_e32 v112, v112, v124
	v_mul_f32_e32 v112, v116, v112
	v_lshlrev_b64 v[116:117], 10, v[114:115]
	v_lshl_add_u64 v[116:117], v[116:117], 0, v[144:145]
	v_lshlrev_b64 v[118:119], 1, v[116:117]
	v_lshl_add_u64 v[116:117], s[68:69], 0, v[118:119]
	v_lshl_add_u64 v[118:119], s[8:9], 0, v[118:119]
	global_load_dwordx2 v[126:127], v[116:117], off
	global_load_dwordx2 v[128:129], v[118:119], off
	global_load_dwordx2 v[198:199], v[116:117], off offset:32
	global_load_dwordx2 v[200:201], v[118:119], off offset:32
	global_load_dwordx2 v[202:203], v[116:117], off offset:64
	global_load_dwordx2 v[204:205], v[118:119], off offset:64
	global_load_dwordx2 v[206:207], v[116:117], off offset:96
	global_load_dwordx2 v[208:209], v[118:119], off offset:96
	global_load_dwordx2 v[210:211], v[116:117], off offset:128
	global_load_dwordx2 v[212:213], v[118:119], off offset:128
	global_load_dwordx2 v[214:215], v[116:117], off offset:160
	global_load_dwordx2 v[216:217], v[118:119], off offset:160
	global_load_dwordx2 v[218:219], v[116:117], off offset:192
	global_load_dwordx2 v[220:221], v[118:119], off offset:192
	global_load_dwordx2 v[222:223], v[116:117], off offset:224
	global_load_dwordx2 v[224:225], v[118:119], off offset:224
	v_pk_mul_f32 v[120:121], v[120:121], v[124:125] op_sel_hi:[1,0]
	v_lshlrev_b64 v[114:115], 12, v[114:115]
	v_lshl_add_u64 v[114:115], s[68:69], 0, v[114:115]
	v_lshl_add_u64 v[114:115], v[114:115], 0, s[2:3]
	v_lshl_add_u64 v[122:123], v[114:115], 0, v[146:147]
	v_lshl_add_u64 v[114:115], v[122:123], 0, s[18:19]
	s_mov_b32 s3, s11
	v_writelane_b32 v255, s0, 50
	s_mov_b32 s0, s7
	s_mov_b32 s2, s6
	s_waitcnt vmcnt(15)
	v_lshlrev_b32_e32 v130, 16, v126
	s_waitcnt vmcnt(14)
	v_and_b32_e32 v131, 0xffff0000, v128
	v_lshlrev_b32_e32 v124, 16, v128
	v_and_b32_e32 v125, 0xffff0000, v126
	v_pk_mul_f32 v[130:131], v[120:121], v[130:131] op_sel:[1,0] op_sel_hi:[0,1]
	v_pk_fma_f32 v[124:125], v[120:121], v[124:125], v[130:131]
	v_lshlrev_b32_e32 v126, 16, v127
	v_pk_fma_f32 v[108:109], v[108:109], v[112:113], v[124:125] op_sel_hi:[1,0,1]
	v_and_b32_e32 v125, 0xffff0000, v127
	v_and_b32_e32 v127, 0xffff0000, v129
	v_lshlrev_b32_e32 v124, 16, v129
	v_pk_mul_f32 v[126:127], v[120:121], v[126:127] op_sel:[1,0] op_sel_hi:[0,1]
	v_pk_fma_f32 v[124:125], v[120:121], v[124:125], v[126:127]
	v_cvt_pk_bf16_f32 v108, v108, v109
	v_pk_fma_f32 v[110:111], v[110:111], v[112:113], v[124:125] op_sel_hi:[1,0,1]
	s_nop 0
	v_cvt_pk_bf16_f32 v109, v110, v111
	v_add_co_u32_e32 v110, vcc, s20, v122
	s_nop 1
	v_addc_co_u32_e32 v111, vcc, 0, v123, vcc
	global_store_dwordx2 v[110:111], v[108:109], off offset:2048
	s_waitcnt vmcnt(13)
; __device__ __forceinline__ unsigned cvtpk(float lo, float hi) { f32x2 v = {lo, hi}; bf16x2_t b = __builtin_convertvector(v, bf16x2_t); return __builtin_bit_cast(unsigned, b); }
; __device__ __forceinline__ void attn_units(const Params& p, LAS unsigned char* buf, int sel, int wave) {
;     ...
; #pragma unroll
;                 for (int d = 0; d < 8; ++d) { const size_t off = m * 1024 + h * 128 + 16 * d + 4 * g;
;                     const u32x2 x0 = *(const u32x2*)(OBR + off), x1 = *(const u32x2*)(OBR + (size_t)MTOK * 1024 + off);
;                     const f32x4 o = oacc[d][qt];
;                     const float r0 = a0 * bflo(x0.x) + a1 * bflo(x1.x) + a2 * o[0], r1 = a0 * bfhi(x0.x) + a1 * bfhi(x1.x) + a2 * o[1];
;                     const float r2 = a0 * bflo(x0.y) + a1 * bflo(x1.y) + a2 * o[2], r3 = a0 * bfhi(x0.y) + a1 * bfhi(x1.y) + a2 * o[3];
;                     u32x2 w; w.x = cvtpk(r0, r1); w.y = cvtpk(r2, r3);
;                     *(u32x2*)(OA + m * DM + 1024 + h * 128 + 16 * d + 4 * g) = w; }
	s_nop 0
	v_mov_b32_e32 v108, v198
	v_mov_b32_e32 v109, v199
	s_nop 0
	v_mov_b32_e32 v110, v200
	v_mov_b32_e32 v111, v201
	v_lshlrev_b32_e32 v124, 16, v108
	v_and_b32_e32 v125, 0xffff0000, v110
	v_lshlrev_b32_e32 v122, 16, v110
	v_and_b32_e32 v123, 0xffff0000, v108
	v_pk_mul_f32 v[124:125], v[120:121], v[124:125] op_sel:[1,0] op_sel_hi:[0,1]
	v_pk_fma_f32 v[122:123], v[120:121], v[122:123], v[124:125]
	v_lshlrev_b32_e32 v108, 16, v109
	v_pk_fma_f32 v[104:105], v[104:105], v[112:113], v[122:123] op_sel_hi:[1,0,1]
	v_and_b32_e32 v123, 0xffff0000, v109
	v_and_b32_e32 v109, 0xffff0000, v111
	v_lshlrev_b32_e32 v122, 16, v111
	v_pk_mul_f32 v[108:109], v[120:121], v[108:109] op_sel:[1,0] op_sel_hi:[0,1]
	v_pk_fma_f32 v[108:109], v[120:121], v[122:123], v[108:109]
	v_cvt_pk_bf16_f32 v104, v104, v105
	v_pk_fma_f32 v[106:107], v[106:107], v[112:113], v[108:109] op_sel_hi:[1,0,1]
	s_nop 0
	v_cvt_pk_bf16_f32 v105, v106, v107
	global_store_dwordx2 v[114:115], v[104:105], off offset:32
	s_waitcnt vmcnt(12)
	s_nop 0
	v_mov_b32_e32 v104, v202
	v_mov_b32_e32 v105, v203
	s_nop 0
	v_mov_b32_e32 v106, v204
	v_mov_b32_e32 v107, v205
	v_lshlrev_b32_e32 v110, 16, v104
	v_and_b32_e32 v111, 0xffff0000, v106
	v_lshlrev_b32_e32 v108, 16, v106
	v_and_b32_e32 v109, 0xffff0000, v104
	v_pk_mul_f32 v[110:111], v[120:121], v[110:111] op_sel:[1,0] op_sel_hi:[0,1]
	v_pk_fma_f32 v[108:109], v[120:121], v[108:109], v[110:111]
	v_lshlrev_b32_e32 v104, 16, v105
	v_pk_fma_f32 v[100:101], v[100:101], v[112:113], v[108:109] op_sel_hi:[1,0,1]
	v_and_b32_e32 v109, 0xffff0000, v105
	v_and_b32_e32 v105, 0xffff0000, v107
	v_lshlrev_b32_e32 v108, 16, v107
	v_pk_mul_f32 v[104:105], v[120:121], v[104:105] op_sel:[1,0] op_sel_hi:[0,1]
	v_pk_fma_f32 v[104:105], v[120:121], v[108:109], v[104:105]
	v_cvt_pk_bf16_f32 v100, v100, v101
	v_pk_fma_f32 v[102:103], v[102:103], v[112:113], v[104:105] op_sel_hi:[1,0,1]
	s_nop 0
	v_cvt_pk_bf16_f32 v101, v102, v103
	global_store_dwordx2 v[114:115], v[100:101], off offset:64
	s_waitcnt vmcnt(11)
	s_nop 0
	v_mov_b32_e32 v100, v206
	v_mov_b32_e32 v101, v207
	s_nop 0
	v_mov_b32_e32 v102, v208
	v_mov_b32_e32 v103, v209
	v_lshlrev_b32_e32 v106, 16, v100
	v_and_b32_e32 v107, 0xffff0000, v102
	v_lshlrev_b32_e32 v104, 16, v102
	v_and_b32_e32 v105, 0xffff0000, v100
	v_pk_mul_f32 v[106:107], v[120:121], v[106:107] op_sel:[1,0] op_sel_hi:[0,1]
	v_pk_fma_f32 v[104:105], v[120:121], v[104:105], v[106:107]
	v_lshlrev_b32_e32 v100, 16, v101
	v_pk_fma_f32 v[96:97], v[96:97], v[112:113], v[104:105] op_sel_hi:[1,0,1]
	v_and_b32_e32 v105, 0xffff0000, v101
	v_and_b32_e32 v101, 0xffff0000, v103
	v_lshlrev_b32_e32 v104, 16, v103
	v_pk_mul_f32 v[100:101], v[120:121], v[100:101] op_sel:[1,0] op_sel_hi:[0,1]
	v_pk_fma_f32 v[100:101], v[120:121], v[104:105], v[100:101]
	v_cvt_pk_bf16_f32 v96, v96, v97
	v_pk_fma_f32 v[98:99], v[98:99], v[112:113], v[100:101] op_sel_hi:[1,0,1]
	s_nop 0
	v_cvt_pk_bf16_f32 v97, v98, v99
	global_store_dwordx2 v[114:115], v[96:97], off offset:96
	s_waitcnt vmcnt(10)
	s_nop 0
	v_mov_b32_e32 v96, v210
	v_mov_b32_e32 v97, v211
	s_nop 0
	v_mov_b32_e32 v98, v212
	v_mov_b32_e32 v99, v213
	v_lshlrev_b32_e32 v102, 16, v96
	v_and_b32_e32 v103, 0xffff0000, v98
	v_lshlrev_b32_e32 v100, 16, v98
	v_and_b32_e32 v101, 0xffff0000, v96
	v_pk_mul_f32 v[102:103], v[120:121], v[102:103] op_sel:[1,0] op_sel_hi:[0,1]
	v_pk_fma_f32 v[100:101], v[120:121], v[100:101], v[102:103]
	v_lshlrev_b32_e32 v96, 16, v97
	v_pk_fma_f32 v[92:93], v[92:93], v[112:113], v[100:101] op_sel_hi:[1,0,1]
	v_and_b32_e32 v101, 0xffff0000, v97
	v_and_b32_e32 v97, 0xffff0000, v99
	v_lshlrev_b32_e32 v100, 16, v99
	v_pk_mul_f32 v[96:97], v[120:121], v[96:97] op_sel:[1,0] op_sel_hi:[0,1]
	v_pk_fma_f32 v[96:97], v[120:121], v[100:101], v[96:97]
	v_cvt_pk_bf16_f32 v92, v92, v93
	v_pk_fma_f32 v[94:95], v[94:95], v[112:113], v[96:97] op_sel_hi:[1,0,1]
	s_nop 0
	v_cvt_pk_bf16_f32 v93, v94, v95
	global_store_dwordx2 v[114:115], v[92:93], off offset:128
	s_waitcnt vmcnt(9)
	s_nop 0
	v_mov_b32_e32 v92, v214
	v_mov_b32_e32 v93, v215
	s_nop 0
	v_mov_b32_e32 v94, v216
	v_mov_b32_e32 v95, v217
	v_lshlrev_b32_e32 v98, 16, v92
	v_and_b32_e32 v99, 0xffff0000, v94
	v_lshlrev_b32_e32 v96, 16, v94
	v_and_b32_e32 v97, 0xffff0000, v92
	v_pk_mul_f32 v[98:99], v[120:121], v[98:99] op_sel:[1,0] op_sel_hi:[0,1]
	v_pk_fma_f32 v[96:97], v[120:121], v[96:97], v[98:99]
	v_lshlrev_b32_e32 v92, 16, v93
	v_pk_fma_f32 v[88:89], v[88:89], v[112:113], v[96:97] op_sel_hi:[1,0,1]
	v_and_b32_e32 v97, 0xffff0000, v93
	v_and_b32_e32 v93, 0xffff0000, v95
	v_lshlrev_b32_e32 v96, 16, v95
	v_pk_mul_f32 v[92:93], v[120:121], v[92:93] op_sel:[1,0] op_sel_hi:[0,1]
	v_pk_fma_f32 v[92:93], v[120:121], v[96:97], v[92:93]
	v_cvt_pk_bf16_f32 v88, v88, v89
	v_pk_fma_f32 v[90:91], v[90:91], v[112:113], v[92:93] op_sel_hi:[1,0,1]
	s_nop 0
	v_cvt_pk_bf16_f32 v89, v90, v91
	global_store_dwordx2 v[114:115], v[88:89], off offset:160
	s_waitcnt vmcnt(8)
	s_nop 0
	v_mov_b32_e32 v88, v218
	v_mov_b32_e32 v89, v219
	s_nop 0
	v_mov_b32_e32 v90, v220
	v_mov_b32_e32 v91, v221
	v_lshlrev_b32_e32 v94, 16, v88
	v_and_b32_e32 v95, 0xffff0000, v90
	v_lshlrev_b32_e32 v92, 16, v90
	v_and_b32_e32 v93, 0xffff0000, v88
	v_pk_mul_f32 v[94:95], v[120:121], v[94:95] op_sel:[1,0] op_sel_hi:[0,1]
	v_pk_fma_f32 v[92:93], v[120:121], v[92:93], v[94:95]
	v_lshlrev_b32_e32 v88, 16, v89
	v_pk_fma_f32 v[84:85], v[84:85], v[112:113], v[92:93] op_sel_hi:[1,0,1]
	v_and_b32_e32 v93, 0xffff0000, v89
	v_and_b32_e32 v89, 0xffff0000, v91
	v_lshlrev_b32_e32 v92, 16, v91
	v_pk_mul_f32 v[88:89], v[120:121], v[88:89] op_sel:[1,0] op_sel_hi:[0,1]
	v_pk_fma_f32 v[88:89], v[120:121], v[92:93], v[88:89]
	v_cvt_pk_bf16_f32 v84, v84, v85
	v_pk_fma_f32 v[86:87], v[86:87], v[112:113], v[88:89] op_sel_hi:[1,0,1]
	s_nop 0
	v_cvt_pk_bf16_f32 v85, v86, v87
	global_store_dwordx2 v[114:115], v[84:85], off offset:192
	s_waitcnt vmcnt(7)
	s_nop 0
	v_mov_b32_e32 v84, v222
	v_mov_b32_e32 v85, v223
	s_nop 0
	v_mov_b32_e32 v86, v224
	v_mov_b32_e32 v87, v225
	v_lshlrev_b32_e32 v90, 16, v84
	v_and_b32_e32 v91, 0xffff0000, v86
	v_lshlrev_b32_e32 v88, 16, v86
	v_and_b32_e32 v89, 0xffff0000, v84
	v_pk_mul_f32 v[90:91], v[120:121], v[90:91] op_sel:[1,0] op_sel_hi:[0,1]
	v_pk_fma_f32 v[88:89], v[120:121], v[88:89], v[90:91]
	v_lshlrev_b32_e32 v84, 16, v85
	v_pk_fma_f32 v[80:81], v[80:81], v[112:113], v[88:89] op_sel_hi:[1,0,1]
	v_and_b32_e32 v89, 0xffff0000, v85
	v_and_b32_e32 v85, 0xffff0000, v87
	v_lshlrev_b32_e32 v88, 16, v87
	v_pk_mul_f32 v[84:85], v[120:121], v[84:85] op_sel:[1,0] op_sel_hi:[0,1]
	v_pk_fma_f32 v[84:85], v[120:121], v[88:89], v[84:85]
	v_cvt_pk_bf16_f32 v80, v80, v81
	v_pk_fma_f32 v[82:83], v[82:83], v[112:113], v[84:85] op_sel_hi:[1,0,1]
	s_nop 0
	v_cvt_pk_bf16_f32 v81, v82, v83
	global_store_dwordx2 v[114:115], v[80:81], off offset:224
	s_cbranch_scc1 .LBB0_773
